# MIX3: RG-LRU output items interleaved into the HGRN2 output item loop (loads at phase A start into unused registers, arithmetic + stores at phase C end); original latency-bound round skipped
# speedup vs baseline: 1.0077x; 1.0069x over previous
.LBB0_53:
	s_and_b64 vcc, exec, s[6:7]
	s_cbranch_vccz .LBB0_334
	v_writelane_b32 v254, s12, 56
	s_cmp_gt_i32 s52, 5
	s_mov_b64 s[6:7], -1
	v_writelane_b32 v254, s13, 57
	s_cbranch_scc0 .LBB0_291
	s_mov_b32 s101, 0
	s_cmpk_lg_i32 s60, 0x100
	s_cbranch_scc0 .LBB0_66
	v_readlane_b32 s6, v254, 39
	v_readlane_b32 s7, v254, 40
	s_and_b64 s[6:7], s[6:7], exec
	s_movk_i32 s3, 0x420
	s_cselect_b32 s3, s3, 0x400
	s_ashr_i32 s61, s60, 31
	s_mul_hi_i32 s7, s3, s94
	s_mul_i32 s6, s3, s94
	s_or_b64 s[8:9], s[6:7], s[60:61]
	s_mov_b32 s8, s81
	s_cmp_lg_u64 s[8:9], 0
	s_cbranch_scc0 .LBB0_61
	s_ashr_i32 s8, s61, 31
	s_add_u32 s10, s60, s8
	s_mov_b32 s9, s8
	s_addc_u32 s11, s61, s8
	s_xor_b64 s[10:11], s[10:11], s[8:9]
	v_cvt_f32_u32_e32 v0, s10
	s_waitcnt vmcnt(0)
	v_cvt_f32_u32_e32 v2, s11
	s_sub_u32 s14, 0, s10
	s_subb_u32 s15, 0, s11
	v_fmac_f32_e32 v0, 0x4f800000, v2
	v_rcp_f32_e32 v0, v0
	s_nop 0
	v_mul_f32_e32 v0, 0x5f7ffffc, v0
	v_mul_f32_e32 v2, 0x2f800000, v0
	v_trunc_f32_e32 v2, v2
	v_fmac_f32_e32 v0, 0xcf800000, v2
	v_cvt_u32_f32_e32 v2, v2
	v_cvt_u32_f32_e32 v0, v0
	v_readfirstlane_b32 s16, v2
	v_readfirstlane_b32 s12, v0
	s_mul_i32 s13, s14, s16
	s_mul_hi_u32 s18, s14, s12
	s_mul_i32 s17, s15, s12
	s_add_i32 s13, s18, s13
	s_add_i32 s13, s13, s17
	s_mul_i32 s19, s14, s12
	s_mul_i32 s18, s12, s13
	s_mul_hi_u32 s20, s12, s19
	s_mul_hi_u32 s17, s12, s13
	s_add_u32 s18, s20, s18
	s_addc_u32 s17, 0, s17
	s_mul_hi_u32 s21, s16, s19
	s_mul_i32 s19, s16, s19
	s_add_u32 s18, s18, s19
	s_mul_hi_u32 s20, s16, s13
	s_addc_u32 s17, s17, s21
	s_addc_u32 s18, s20, 0
	s_mul_i32 s13, s16, s13
	s_add_u32 s13, s17, s13
	s_addc_u32 s17, 0, s18
	s_add_u32 s18, s12, s13
	s_cselect_b64 s[12:13], -1, 0
	s_cmp_lg_u64 s[12:13], 0
	s_addc_u32 s16, s16, s17
	s_mul_i32 s12, s14, s16
	s_mul_hi_u32 s13, s14, s18
	s_add_i32 s12, s13, s12
	s_mul_i32 s15, s15, s18
	s_add_i32 s12, s12, s15
	s_mul_i32 s14, s14, s18
	s_mul_hi_u32 s15, s16, s14
	s_mul_i32 s17, s16, s14
	s_mul_i32 s20, s18, s12
	s_mul_hi_u32 s14, s18, s14
	s_mul_hi_u32 s19, s18, s12
	s_add_u32 s14, s14, s20
	s_addc_u32 s19, 0, s19
	s_add_u32 s14, s14, s17
	s_mul_hi_u32 s13, s16, s12
	s_addc_u32 s14, s19, s15
	s_addc_u32 s13, s13, 0
	s_mul_i32 s12, s16, s12
	s_add_u32 s12, s14, s12
	s_addc_u32 s14, 0, s13
	s_add_u32 s17, s18, s12
	s_cselect_b64 s[12:13], -1, 0
	s_cmp_lg_u64 s[12:13], 0
	s_addc_u32 s16, s16, s14
	s_ashr_i32 s12, s7, 31
	s_add_u32 s14, s6, s12
	s_mov_b32 s13, s12
	s_addc_u32 s15, s7, s12
	s_xor_b64 s[14:15], s[14:15], s[12:13]
	s_mul_i32 s18, s14, s16
	s_mul_hi_u32 s19, s14, s17
	s_mul_hi_u32 s7, s14, s16
	s_add_u32 s18, s19, s18
	s_addc_u32 s7, 0, s7
	s_mul_hi_u32 s20, s15, s17
	s_mul_i32 s17, s15, s17
	s_add_u32 s17, s18, s17
	s_mul_hi_u32 s19, s15, s16
	s_addc_u32 s7, s7, s20
	s_addc_u32 s17, s19, 0
	s_mul_i32 s16, s15, s16
	s_add_u32 s7, s7, s16
	s_addc_u32 s20, 0, s17
	s_mul_i32 s16, s10, s20
	s_mul_hi_u32 s17, s10, s7
	s_add_i32 s16, s17, s16
	s_mul_i32 s17, s11, s7
	s_add_i32 s21, s16, s17
	s_sub_i32 s18, s15, s21
	s_mul_i32 s16, s10, s7
	s_sub_u32 s14, s14, s16
	s_cselect_b64 s[16:17], -1, 0
	s_cmp_lg_u64 s[16:17], 0
	s_subb_u32 s22, s18, s11
	s_sub_u32 s23, s14, s10
	s_cselect_b64 s[18:19], -1, 0
	s_cmp_lg_u64 s[18:19], 0
	s_subb_u32 s18, s22, 0
	s_cmp_ge_u32 s18, s11
	s_cselect_b32 s19, -1, 0
	s_cmp_ge_u32 s23, s10
	s_cselect_b32 s22, -1, 0
	s_cmp_eq_u32 s18, s11
	s_cselect_b32 s18, s22, s19
	s_add_u32 s19, s7, 1
	s_addc_u32 s22, s20, 0
	s_add_u32 s23, s7, 2
	s_addc_u32 s24, s20, 0
	s_cmp_lg_u32 s18, 0
	s_cselect_b32 s18, s23, s19
	s_cselect_b32 s19, s24, s22
	s_cmp_lg_u64 s[16:17], 0
	s_subb_u32 s15, s15, s21
	s_cmp_ge_u32 s15, s11
	s_cselect_b32 s16, -1, 0
	s_cmp_ge_u32 s14, s10
	s_cselect_b32 s10, -1, 0
	s_cmp_eq_u32 s15, s11
	s_cselect_b32 s10, s10, s16
	s_cmp_lg_u32 s10, 0
	s_cselect_b32 s11, s19, s20
	s_cselect_b32 s10, s18, s7
	s_xor_b64 s[8:9], s[12:13], s[8:9]
	s_xor_b64 s[10:11], s[10:11], s[8:9]
	s_sub_u32 s52, s10, s8
	v_cvt_f32_u32_e32 v0, s60
	s_cbranch_execnz .LBB0_59

.LBB0_68:
	s_waitcnt vmcnt(0)
	v_mov_b32_e32 v3, v244
	s_cmp_ge_i32 s52, s70
	v_readfirstlane_b32 s3, v3
	s_cbranch_scc1 .LBB0_123
	s_cmp_eq_u64 s[4:5], 0
	s_cbranch_scc0 .Lrgi_l1
	s_sub_i32 s100, s94, 32
	s_cmp_lt_i32 s94, 32
	s_cbranch_scc0 .Lrgi_done
	s_mov_b32 s100, -1
	s_branch .Lrgi_done
.Lrgi_l1:
	s_sub_i32 s100, 0xff, s94
.Lrgi_done:
	s_mov_b64 s[12:13], -1
	s_and_b64 vcc, exec, s[4:5]
	s_mov_b64 s[6:7], -1
	s_cbranch_vccz .LBB0_71
	s_ashr_i32 s19, s52, 7
	s_and_b32 s18, s52, 0x7f
	s_cbranch_execnz .LBB0_73
	s_branch .LBB0_72

.LBB0_82:
	s_nop 10
	ds_write_b128 v140, v[2:5]
	ds_write_b128 v140, v[6:9] offset:32
	ds_write_b128 v140, v[10:13] offset:64
	ds_write_b128 v140, v[14:17] offset:96
	s_waitcnt lgkmcnt(0)
	s_barrier
	ds_read_b128 v[2:5], v133
	ds_read_b128 v[6:9], v132
	ds_read_b128 v[10:13], v132 offset:16
	ds_read_b128 v[14:17], v133 offset:16
	s_mov_b32 s52, s3
	s_waitcnt lgkmcnt(2)
	v_pk_add_f32 v[2:3], v[6:7], v[2:3]
	v_pk_add_f32 v[4:5], v[8:9], v[4:5]
	s_waitcnt lgkmcnt(0)
	v_pk_add_f32 v[6:7], v[12:13], v[16:17]
	v_pk_mul_f32 v[12:13], v[2:3], v[2:3]
	v_pk_add_f32 v[8:9], v[10:11], v[14:15]
	v_pk_mul_f32 v[10:11], v[4:5], v[4:5]
	v_add_f32_e32 v12, v12, v13
	v_add_f32_e32 v10, v10, v12
	v_pk_mul_f32 v[16:17], v[8:9], v[8:9]
	v_add_f32_e32 v10, v11, v10
	v_add_f32_e32 v10, v16, v10
	v_pk_mul_f32 v[14:15], v[6:7], v[6:7]
	v_add_f32_e32 v10, v17, v10
	v_add_f32_e32 v10, v14, v10
	v_add_f32_e32 v10, v15, v10
	v_mov_b32_e32 v11, v10
	s_nop 1
	v_mov_b32_dpp v11, v11 quad_perm:[1,0,3,2] row_mask:0xf bank_mask:0xf
	v_add_f32_e32 v10, v10, v11
	v_mov_b32_e32 v11, v10
	s_nop 1
	v_mov_b32_dpp v11, v11 quad_perm:[2,3,0,1] row_mask:0xf bank_mask:0xf
	v_add_f32_e32 v10, v10, v11
	v_mov_b32_e32 v11, v10
	s_nop 1
	v_mov_b32_dpp v11, v11 row_half_mirror row_mask:0xf bank_mask:0xf
	v_add_f32_e32 v10, v10, v11
	v_fmamk_f32 v10, v10, 0x3c800000, v218
	v_mul_f32_e32 v11, 0x4b800000, v10
	v_cmp_gt_f32_e32 vcc, s86, v10
	s_nop 1
	v_cndmask_b32_e32 v10, v10, v11, vcc
	v_rsq_f32_e32 v10, v10
	s_nop 0
	v_mul_f32_e32 v11, 0x45800000, v10
	v_cndmask_b32_e32 v10, v10, v11, vcc
	v_mul_f32_e32 v2, v2, v10
	s_waitcnt vmcnt(0)
	v_mul_f32_e32 v2, v74, v2
	v_lshlrev_b32_e32 v11, 16, v66
	v_mul_f32_e32 v3, v3, v10
	v_mul_f32_e32 v2, v2, v11
	v_mul_f32_e32 v3, v75, v3
	v_and_b32_e32 v11, 0xffff0000, v66
	v_mul_f32_e32 v3, v3, v11
	v_cvt_pk_bf16_f32 v2, v2, v3
	v_mul_f32_e32 v3, v4, v10
	v_mul_f32_e32 v3, v76, v3
	v_lshlrev_b32_e32 v4, 16, v67
	v_mul_f32_e32 v3, v3, v4
	v_mul_f32_e32 v4, v5, v10
	v_mul_f32_e32 v4, v77, v4
	v_and_b32_e32 v5, 0xffff0000, v67
	v_mul_f32_e32 v4, v4, v5
	v_cvt_pk_bf16_f32 v3, v3, v4
	v_mul_f32_e32 v4, v8, v10
	v_mul_f32_e32 v4, v70, v4
	v_lshlrev_b32_e32 v5, 16, v68
	v_mul_f32_e32 v4, v4, v5
	v_mul_f32_e32 v5, v9, v10
	v_mul_f32_e32 v5, v71, v5
	v_and_b32_e32 v8, 0xffff0000, v68
	v_mul_f32_e32 v5, v5, v8
	v_cvt_pk_bf16_f32 v4, v4, v5
	v_mul_f32_e32 v5, v6, v10
	v_mul_f32_e32 v5, v72, v5
	v_lshlrev_b32_e32 v6, 16, v69
	v_mul_f32_e32 v5, v5, v6
	v_mul_f32_e32 v6, v7, v10
	v_mul_f32_e32 v6, v73, v6
	v_and_b32_e32 v7, 0xffff0000, v69
	v_mul_f32_e32 v6, v6, v7
	v_cvt_pk_bf16_f32 v5, v5, v6
	v_lshlrev_b64 v[6:7], 11, v[104:105]
	v_lshl_add_u64 v[6:7], s[92:93], 0, v[6:7]
	v_lshl_add_u64 v[6:7], v[6:7], 0, s[80:81]
	v_lshl_add_u64 v[6:7], v[6:7], 0, v[0:1]
	s_cmp_eq_u32 s100, -1
	s_cbranch_scc1 .Lrgb_skip
	s_waitcnt vmcnt(0)
	v_and_b32_e32 v157, 0xffff0000, v168
	v_lshlrev_b32_e32 v168, 16, v168
	v_fma_f32 v168, v200, v157, v168
	v_and_b32_e32 v158, 0xffff0000, v184
	v_lshlrev_b32_e32 v184, 16, v184
	v_fma_f32 v184, v220, v158, v184
	v_add_f32_e32 v168, v168, v184
	v_and_b32_e32 v157, 0xffff0000, v169
	v_lshlrev_b32_e32 v169, 16, v169
	v_fma_f32 v169, v201, v157, v169
	v_and_b32_e32 v158, 0xffff0000, v185
	v_lshlrev_b32_e32 v185, 16, v185
	v_fma_f32 v185, v221, v158, v185
	v_add_f32_e32 v169, v169, v185
	v_and_b32_e32 v157, 0xffff0000, v170
	v_lshlrev_b32_e32 v170, 16, v170
	v_fma_f32 v170, v202, v157, v170
	v_and_b32_e32 v158, 0xffff0000, v186
	v_lshlrev_b32_e32 v186, 16, v186
	v_fma_f32 v186, v222, v158, v186
	v_add_f32_e32 v170, v170, v186
	v_and_b32_e32 v157, 0xffff0000, v171
	v_lshlrev_b32_e32 v171, 16, v171
	v_fma_f32 v171, v203, v157, v171
	v_and_b32_e32 v158, 0xffff0000, v187
	v_lshlrev_b32_e32 v187, 16, v187
	v_fma_f32 v187, v223, v158, v187
	v_add_f32_e32 v171, v171, v187
	v_and_b32_e32 v157, 0xffff0000, v172
	v_lshlrev_b32_e32 v172, 16, v172
	v_fma_f32 v172, v204, v157, v172
	v_and_b32_e32 v158, 0xffff0000, v188
	v_lshlrev_b32_e32 v188, 16, v188
	v_fma_f32 v188, v224, v158, v188
	v_add_f32_e32 v172, v172, v188
	v_and_b32_e32 v157, 0xffff0000, v173
	v_lshlrev_b32_e32 v173, 16, v173
	v_fma_f32 v173, v205, v157, v173
	v_and_b32_e32 v158, 0xffff0000, v189
	v_lshlrev_b32_e32 v189, 16, v189
	v_fma_f32 v189, v225, v158, v189
	v_add_f32_e32 v173, v173, v189
	v_and_b32_e32 v157, 0xffff0000, v174
	v_lshlrev_b32_e32 v174, 16, v174
	v_fma_f32 v174, v206, v157, v174
	v_and_b32_e32 v158, 0xffff0000, v190
	v_lshlrev_b32_e32 v190, 16, v190
	v_fma_f32 v190, v226, v158, v190
	v_add_f32_e32 v174, v174, v190
	v_and_b32_e32 v157, 0xffff0000, v175
	v_lshlrev_b32_e32 v175, 16, v175
	v_fma_f32 v175, v207, v157, v175
	v_and_b32_e32 v158, 0xffff0000, v191
	v_lshlrev_b32_e32 v191, 16, v191
	v_fma_f32 v191, v227, v158, v191
	v_add_f32_e32 v175, v175, v191
	v_and_b32_e32 v157, 0xffff0000, v176
	v_lshlrev_b32_e32 v176, 16, v176
	v_fma_f32 v176, v208, v157, v176
	v_and_b32_e32 v158, 0xffff0000, v192
	v_lshlrev_b32_e32 v192, 16, v192
	v_fma_f32 v192, v228, v158, v192
	v_add_f32_e32 v176, v176, v192
	v_and_b32_e32 v157, 0xffff0000, v177
	v_lshlrev_b32_e32 v177, 16, v177
	v_fma_f32 v177, v209, v157, v177
	v_and_b32_e32 v158, 0xffff0000, v193
	v_lshlrev_b32_e32 v193, 16, v193
	v_fma_f32 v193, v229, v158, v193
	v_add_f32_e32 v177, v177, v193
	v_and_b32_e32 v157, 0xffff0000, v178
	v_lshlrev_b32_e32 v178, 16, v178
	v_fma_f32 v178, v210, v157, v178
	v_and_b32_e32 v158, 0xffff0000, v194
	v_lshlrev_b32_e32 v194, 16, v194
	v_fma_f32 v194, v230, v158, v194
	v_add_f32_e32 v178, v178, v194
	v_and_b32_e32 v157, 0xffff0000, v179
	v_lshlrev_b32_e32 v179, 16, v179
	v_fma_f32 v179, v211, v157, v179
	v_and_b32_e32 v158, 0xffff0000, v195
	v_lshlrev_b32_e32 v195, 16, v195
	v_fma_f32 v195, v231, v158, v195
	v_add_f32_e32 v179, v179, v195
	v_and_b32_e32 v157, 0xffff0000, v180
	v_lshlrev_b32_e32 v180, 16, v180
	v_fma_f32 v180, v212, v157, v180
	v_and_b32_e32 v158, 0xffff0000, v196
	v_lshlrev_b32_e32 v196, 16, v196
	v_fma_f32 v196, v232, v158, v196
	v_add_f32_e32 v180, v180, v196
	v_and_b32_e32 v157, 0xffff0000, v181
	v_lshlrev_b32_e32 v181, 16, v181
	v_fma_f32 v181, v213, v157, v181
	v_and_b32_e32 v158, 0xffff0000, v197
	v_lshlrev_b32_e32 v197, 16, v197
	v_fma_f32 v197, v233, v158, v197
	v_add_f32_e32 v181, v181, v197
	v_and_b32_e32 v157, 0xffff0000, v182
	v_lshlrev_b32_e32 v182, 16, v182
	v_fma_f32 v182, v214, v157, v182
	v_and_b32_e32 v158, 0xffff0000, v198
	v_lshlrev_b32_e32 v198, 16, v198
	v_fma_f32 v198, v234, v158, v198
	v_add_f32_e32 v182, v182, v198
	v_and_b32_e32 v157, 0xffff0000, v183
	v_lshlrev_b32_e32 v183, 16, v183
	v_fma_f32 v183, v215, v157, v183
	v_and_b32_e32 v158, 0xffff0000, v199
	v_lshlrev_b32_e32 v199, 16, v199
	v_fma_f32 v199, v235, v158, v199
	v_add_f32_e32 v183, v183, v199
	v_lshlrev_b32_e32 v157, 16, v160
	v_and_b32_e32 v158, 0xffff0000, v160
	v_mul_f32_e32 v157, v168, v157
	v_mul_f32_e32 v158, v169, v158
	v_cvt_pk_bf16_f32 v160, v157, v158
	v_lshlrev_b32_e32 v157, 16, v161
	v_and_b32_e32 v158, 0xffff0000, v161
	v_mul_f32_e32 v157, v170, v157
	v_mul_f32_e32 v158, v171, v158
	v_cvt_pk_bf16_f32 v161, v157, v158
	v_lshlrev_b32_e32 v157, 16, v162
	v_and_b32_e32 v158, 0xffff0000, v162
	v_mul_f32_e32 v157, v172, v157
	v_mul_f32_e32 v158, v173, v158
	v_cvt_pk_bf16_f32 v162, v157, v158
	v_lshlrev_b32_e32 v157, 16, v163
	v_and_b32_e32 v158, 0xffff0000, v163
	v_mul_f32_e32 v157, v174, v157
	v_mul_f32_e32 v158, v175, v158
	v_cvt_pk_bf16_f32 v163, v157, v158
	v_lshlrev_b32_e32 v157, 16, v164
	v_and_b32_e32 v158, 0xffff0000, v164
	v_mul_f32_e32 v157, v176, v157
	v_mul_f32_e32 v158, v177, v158
	v_cvt_pk_bf16_f32 v164, v157, v158
	v_lshlrev_b32_e32 v157, 16, v165
	v_and_b32_e32 v158, 0xffff0000, v165
	v_mul_f32_e32 v157, v178, v157
	v_mul_f32_e32 v158, v179, v158
	v_cvt_pk_bf16_f32 v165, v157, v158
	v_lshlrev_b32_e32 v157, 16, v166
	v_and_b32_e32 v158, 0xffff0000, v166
	v_mul_f32_e32 v157, v180, v157
	v_mul_f32_e32 v158, v181, v158
	v_cvt_pk_bf16_f32 v166, v157, v158
	v_lshlrev_b32_e32 v157, 16, v167
	v_and_b32_e32 v158, 0xffff0000, v167
	v_mul_f32_e32 v157, v182, v157
	v_mul_f32_e32 v158, v183, v158
	v_cvt_pk_bf16_f32 v167, v157, v158
	global_store_dwordx4 v236, v[160:163], s[96:97]
	global_store_dwordx4 v236, v[164:167], s[96:97] offset:16
	s_movk_i32 s98, 0x100
	s_movk_i32 s99, 0x200
	s_cmp_eq_u64 s[4:5], 0
	s_cselect_b32 s98, 0xe0, s98
	s_cselect_b32 s99, 0x210, s99
	s_add_i32 s100, s100, s98
	s_cmp_lt_i32 s100, s99
	s_cbranch_scc1 .Lrgb_skip
	s_mov_b32 s100, -1
	s_mov_b32 s101, 1
.Lrgb_skip:
	s_andn2_b64 vcc, exec, s[78:79]
	global_store_dwordx4 v[6:7], v[2:5], off offset:1024
	s_barrier
	s_cbranch_vccz .LBB0_122

.LBB0_91:
	s_waitcnt vmcnt(0)
	s_cmp_eq_u32 s100, -1
	s_cbranch_scc1 .Lrga_skip
	s_lshr_b32 s98, s100, 1
	s_and_b32 s99, s100, 1
	v_mov_b32_e32 v160, s98
	v_mov_b32_e32 v161, s99
	s_cmp_eq_u64 s[4:5], 0
	s_cbranch_scc0 .Lrga_l1
	v_cmp_le_u32_e32 vcc, 0x84, v160
	s_nop 1
	v_cndmask_b32_e64 v162, 0, 1, vcc
	v_mul_u32_u24_e32 v163, 0x84, v162
	v_sub_u32_e32 v160, v160, v163
	s_branch .Lrga_dec
.Lrga_l1:
	v_lshrrev_b32_e32 v162, 7, v160
	v_and_b32_e32 v160, 0x7f, v160
	v_add_u32_e32 v160, 4, v160
.Lrga_dec:
	v_cmp_gt_u32_e32 vcc, 4, v160
	v_subrev_u32_e32 v163, 4, v160
	v_lshlrev_b32_e32 v164, 8, v162
	v_add_u32_e32 v164, 0x4000, v164
	v_lshlrev_b32_e32 v165, 13, v162
	v_cndmask_b32_e32 v163, v163, v160, vcc
	v_cndmask_b32_e32 v164, v165, v164, vcc
	v_lshl_add_u32 v164, v163, 6, v164
	v_sub_u32_e32 v165, 3, v163
	v_sub_u32_e32 v166, 0x83, v163
	v_cndmask_b32_e32 v165, v166, v165, vcc
	v_lshrrev_b32_e32 v166, 3, v244
	v_and_b32_e32 v167, 7, v244
	v_add_u32_e32 v168, v164, v166
	v_mul_u32_u24_e32 v157, 0x1400, v168
	v_add_u32_e32 v157, 0x7501200, v157
	v_lshl_add_u32 v157, v161, 8, v157
	v_lshl_add_u32 v157, v167, 5, v157
	v_lshlrev_b32_e32 v236, 11, v168
	v_add_u32_e32 v236, 0x5400600, v236
	v_lshl_add_u32 v236, v161, 8, v236
	v_lshl_add_u32 v236, v167, 5, v236
	v_lshl_add_u32 v169, v160, 1, v161
	v_lshlrev_b32_e32 v169, 15, v169
	v_lshl_add_u32 v169, v166, 9, v169
	v_lshl_add_u32 v169, v167, 6, v169
	v_cmp_ne_u32_e32 vcc, 0, v162
	v_mov_b32_e32 v170, 0xe8c0000
	v_mov_b32_e32 v171, 0xe080000
	v_cndmask_b32_e32 v170, v171, v170, vcc
	v_add_u32_e32 v158, v170, v169
	v_mov_b32_e32 v170, 0x12000000
	v_mov_b32_e32 v171, 0xf700000
	v_cndmask_b32_e32 v170, v171, v170, vcc
	v_add_u32_e32 v159, v170, v169
	v_mul_u32_u24_e32 v170, 0x84, v162
	v_add_u32_e32 v171, v170, v160
	v_lshlrev_b32_e32 v171, 10, v171
	v_add_u32_e32 v171, 0xf380000, v171
	v_lshl_add_u32 v171, v161, 9, v171
	v_lshl_add_u32 v216, v167, 6, v171
	v_add_u32_e32 v171, v170, v165
	v_add_u32_e32 v171, 0x108, v171
	v_lshlrev_b32_e32 v171, 10, v171
	v_add_u32_e32 v171, 0xf380000, v171
	v_lshl_add_u32 v171, v161, 9, v171
	v_lshl_add_u32 v217, v167, 6, v171
	global_load_dwordx4 v[160:163], v157, s[96:97]
	global_load_dwordx4 v[164:167], v157, s[96:97] offset:16
	global_load_dwordx4 v[168:171], v158, s[96:97]
	global_load_dwordx4 v[172:175], v158, s[96:97] offset:16
	global_load_dwordx4 v[176:179], v158, s[96:97] offset:32
	global_load_dwordx4 v[180:183], v158, s[96:97] offset:48
	global_load_dwordx4 v[184:187], v159, s[96:97]
	global_load_dwordx4 v[188:191], v159, s[96:97] offset:16
	global_load_dwordx4 v[192:195], v159, s[96:97] offset:32
	global_load_dwordx4 v[196:199], v159, s[96:97] offset:48
	global_load_dwordx4 v[200:203], v216, s[96:97]
	global_load_dwordx4 v[204:207], v216, s[96:97] offset:16
	global_load_dwordx4 v[208:211], v216, s[96:97] offset:32
	global_load_dwordx4 v[212:215], v216, s[96:97] offset:48
	global_load_dwordx4 v[220:223], v217, s[96:97]
	global_load_dwordx4 v[224:227], v217, s[96:97] offset:16
	global_load_dwordx4 v[228:231], v217, s[96:97] offset:32
	global_load_dwordx4 v[232:235], v217, s[96:97] offset:48
.Lrga_skip:
	v_lshlrev_b32_e32 v2, 16, v62
	v_and_b32_e32 v3, 0xffff0000, v62
	v_lshlrev_b32_e32 v4, 16, v63
	v_mul_f32_e32 v18, 0x3fb8aa3b, v2
	v_and_b32_e32 v5, 0xffff0000, v63
	v_lshlrev_b32_e32 v6, 16, v64
	v_exp_f32_e32 v19, v18
	v_mul_f32_e32 v18, 0x3fb8aa3b, v3
	v_mul_f32_e32 v20, 0x3fb8aa3b, v4
	v_and_b32_e32 v7, 0xffff0000, v64
	v_exp_f32_e32 v18, v18
	v_exp_f32_e32 v21, v20
	v_mul_f32_e32 v20, 0x3fb8aa3b, v5
	v_mul_f32_e32 v22, 0x3fb8aa3b, v6
	v_lshlrev_b32_e32 v8, 16, v65
	v_and_b32_e32 v9, 0xffff0000, v65
	v_lshlrev_b32_e32 v10, 16, v58
	v_and_b32_e32 v11, 0xffff0000, v58
	v_lshlrev_b32_e32 v12, 16, v59
	v_and_b32_e32 v13, 0xffff0000, v59
	v_lshlrev_b32_e32 v14, 16, v60
	v_and_b32_e32 v15, 0xffff0000, v60
	v_lshlrev_b32_e32 v16, 16, v61
	v_and_b32_e32 v17, 0xffff0000, v61
	v_exp_f32_e32 v20, v20
	v_exp_f32_e32 v23, v22
	v_mul_f32_e32 v22, 0x3fb8aa3b, v7
	ds_write_b128 v125, v[2:5]
	ds_write_b128 v125, v[6:9] offset:16
	ds_write_b128 v125, v[10:13] offset:32
	ds_write_b128 v125, v[14:17] offset:48
	s_waitcnt lgkmcnt(0)
	s_barrier
	ds_read2_b32 v[2:3], v136 offset1:68
	ds_read2_b32 v[4:5], v136 offset0:136 offset1:204
	v_exp_f32_e32 v22, v22
	v_mul_f32_e32 v24, 0x3fb8aa3b, v8
	v_pk_add_f32 v[74:75], v[18:19], 1.0 op_sel_hi:[1,0] neg_lo:[1,0] neg_hi:[1,0]
	v_add_u32_e32 v18, 0x400, v136
	v_exp_f32_e32 v25, v24
	v_mul_f32_e32 v24, 0x3fb8aa3b, v9
	v_pk_add_f32 v[72:73], v[20:21], 1.0 op_sel_hi:[1,0] neg_lo:[1,0] neg_hi:[1,0]
	ds_read2_b32 v[6:7], v18 offset0:16 offset1:84
	ds_read2_b32 v[8:9], v18 offset0:152 offset1:220
	s_waitcnt lgkmcnt(3)
	v_add_f32_e32 v21, 0, v2
	v_pk_add_f32 v[70:71], v[22:23], 1.0 op_sel_hi:[1,0] neg_lo:[1,0] neg_hi:[1,0]
	v_add_f32_e32 v22, v21, v3
	s_waitcnt lgkmcnt(2)
	v_add_f32_e32 v4, v22, v4
	v_mul_f32_e32 v26, 0x3fb8aa3b, v10
	v_mul_f32_e32 v28, 0x3fb8aa3b, v12
	v_add_u32_e32 v19, 0x800, v136
	v_add_f32_e32 v5, v4, v5
	v_exp_f32_e32 v27, v26
	v_mul_f32_e32 v26, 0x3fb8aa3b, v11
	v_exp_f32_e32 v29, v28
	v_mul_f32_e32 v28, 0x3fb8aa3b, v13
	ds_read2_b32 v[10:11], v19 offset0:32 offset1:100
	ds_read2_b32 v[12:13], v19 offset0:168 offset1:236
	s_waitcnt lgkmcnt(3)
	v_add_f32_e32 v6, v5, v6
	v_add_f32_e32 v7, v6, v7
	s_waitcnt lgkmcnt(2)
	v_add_f32_e32 v8, v7, v8
	v_mul_f32_e32 v30, 0x3fb8aa3b, v14
	v_mul_f32_e32 v32, 0x3fb8aa3b, v16
	v_add_u32_e32 v20, 0xc00, v136
	v_add_f32_e32 v9, v8, v9
	v_exp_f32_e32 v31, v30
	v_mul_f32_e32 v30, 0x3fb8aa3b, v15
	v_exp_f32_e32 v33, v32
	v_mul_f32_e32 v32, 0x3fb8aa3b, v17
	ds_read2_b32 v[14:15], v20 offset0:48 offset1:116
	ds_read2_b32 v[16:17], v20 offset0:184 offset1:252
	s_waitcnt lgkmcnt(3)
	v_add_f32_e32 v10, v9, v10
	v_add_f32_e32 v11, v10, v11
	s_waitcnt lgkmcnt(2)
	v_add_f32_e32 v12, v11, v12
	v_add_f32_e32 v13, v12, v13
	s_waitcnt lgkmcnt(1)
	v_add_f32_e32 v14, v13, v14
	v_add_f32_e32 v15, v14, v15
	s_waitcnt lgkmcnt(0)
	v_add_f32_e32 v16, v15, v16
	v_add_f32_e32 v17, v16, v17
	ds_write_b32 v126, v17
	s_waitcnt lgkmcnt(0)
	s_barrier
	ds_read2st64_b32 v[2:3], v127 offset1:1
	ds_read_b32 v23, v127 offset:512
	v_exp_f32_e32 v24, v24
	v_exp_f32_e32 v26, v26
	v_exp_f32_e32 v28, v28
	s_waitcnt lgkmcnt(1)
	v_cndmask_b32_e64 v2, v2, 0, s[8:9]
	v_cndmask_b32_e64 v3, 0, v3, s[10:11]
	v_add_f32_e32 v2, v2, v3
	s_waitcnt lgkmcnt(0)
	v_cndmask_b32_e64 v3, 0, v23, s[12:13]
	v_add_f32_e32 v2, v2, v3
	v_add_f32_e32 v3, v21, v2
	v_add_f32_e32 v21, v22, v2
	ds_write2_b32 v136, v3, v21 offset1:68
	v_add_f32_e32 v3, v4, v2
	v_add_f32_e32 v4, v5, v2
	ds_write2_b32 v136, v3, v4 offset0:136 offset1:204
	v_add_f32_e32 v3, v6, v2
	v_add_f32_e32 v4, v7, v2
	ds_write2_b32 v18, v3, v4 offset0:16 offset1:84
	v_add_f32_e32 v3, v8, v2
	v_add_f32_e32 v4, v9, v2
	v_exp_f32_e32 v30, v30
	v_exp_f32_e32 v32, v32
	ds_write2_b32 v18, v3, v4 offset0:152 offset1:220
	v_add_f32_e32 v3, v10, v2
	v_add_f32_e32 v4, v11, v2
	ds_write2_b32 v19, v3, v4 offset0:32 offset1:100
	v_add_f32_e32 v3, v12, v2
	v_add_f32_e32 v4, v13, v2
	ds_write2_b32 v19, v3, v4 offset0:168 offset1:236
	v_add_f32_e32 v3, v14, v2
	v_add_f32_e32 v4, v15, v2
	ds_write2_b32 v20, v3, v4 offset0:48 offset1:116
	v_add_f32_e32 v3, v16, v2
	v_add_f32_e32 v2, v17, v2
	v_pk_add_f32 v[68:69], v[24:25], 1.0 op_sel_hi:[1,0] neg_lo:[1,0] neg_hi:[1,0]
	v_pk_add_f32 v[66:67], v[26:27], 1.0 op_sel_hi:[1,0] neg_lo:[1,0] neg_hi:[1,0]
	v_pk_add_f32 v[80:81], v[28:29], 1.0 op_sel_hi:[1,0] neg_lo:[1,0] neg_hi:[1,0]
	v_pk_add_f32 v[78:79], v[30:31], 1.0 op_sel_hi:[1,0] neg_lo:[1,0] neg_hi:[1,0]
	v_pk_add_f32 v[76:77], v[32:33], 1.0 op_sel_hi:[1,0] neg_lo:[1,0] neg_hi:[1,0]
	ds_write2_b32 v20, v3, v2 offset0:184 offset1:252
	s_waitcnt lgkmcnt(0)
	s_barrier
	ds_read_b128 v[26:29], v125
	ds_read_b128 v[18:21], v125 offset:16
	ds_read_b128 v[10:13], v125 offset:32
	ds_read_b128 v[2:5], v125 offset:48
	ds_read_b128 v[30:33], v124 offset:8432
	ds_read_b128 v[22:25], v124 offset:8448
	ds_read_b128 v[14:17], v124 offset:8464
	ds_read_b128 v[6:9], v124 offset:8480
	v_and_b32_e32 v108, 0xffff0000, v50
	v_lshlrev_b32_e32 v109, 16, v50
	v_and_b32_e32 v106, 0xffff0000, v51
	v_lshlrev_b32_e32 v107, 16, v51
	v_and_b32_e32 v104, 0xffff0000, v52
	v_lshlrev_b32_e32 v105, 16, v52
	v_and_b32_e32 v92, 0xffff0000, v53
	v_lshlrev_b32_e32 v93, 16, v53
	v_and_b32_e32 v88, 0xffff0000, v42
	v_lshlrev_b32_e32 v89, 16, v42
	v_and_b32_e32 v86, 0xffff0000, v43
	v_lshlrev_b32_e32 v87, 16, v43
	v_and_b32_e32 v84, 0xffff0000, v44
	v_lshlrev_b32_e32 v85, 16, v44
	v_and_b32_e32 v82, 0xffff0000, v45
	v_lshlrev_b32_e32 v83, 16, v45
	s_waitcnt lgkmcnt(4)
	v_mov_b32_e32 v101, v5
	v_mov_b64_e32 v[90:91], v[82:83]
	v_mov_b64_e32 v[110:111], v[84:85]
	v_mov_b64_e32 v[112:113], v[86:87]
	v_mov_b64_e32 v[114:115], v[88:89]
	v_mov_b64_e32 v[116:117], v[92:93]
	v_mov_b64_e32 v[118:119], v[104:105]
	v_mov_b64_e32 v[120:121], v[106:107]
	v_mov_b64_e32 v[122:123], v[108:109]
	s_and_saveexec_b64 s[62:63], s[14:15]
	s_movk_i32 s90, 0x800
	s_mov_b32 s91, 0x129000
	s_cbranch_execz .LBB0_93
	s_waitcnt lgkmcnt(0)
	v_sub_f32_e32 v101, v9, v5
	v_mov_b64_e32 v[90:91], v[76:77]
	v_mov_b64_e32 v[110:111], v[78:79]
	v_mov_b64_e32 v[112:113], v[80:81]
	v_mov_b64_e32 v[114:115], v[66:67]
	v_mov_b64_e32 v[116:117], v[68:69]
	v_mov_b64_e32 v[118:119], v[70:71]
	v_mov_b64_e32 v[120:121], v[72:73]
	v_mov_b64_e32 v[122:123], v[74:75]

.LBB0_123:
	s_cmp_eq_u32 s101, 1
	s_cbranch_scc0 .Lrg_noskip
	s_waitcnt lgkmcnt(0)
	s_branch .LBB0_289
